# SwiGLU GEMM epilogue: silu(g)*u evaluated stage-wise over 8 independent elements (no dependent chains / wait states), scalar row-address increments
# speedup vs baseline: 1.0022x; 1.0022x over previous
; __device__ __forceinline__ unsigned cvt_pk_bf16(float lo, float hi) { unsigned r; asm volatile("v_cvt_pk_bf16_f32 %0, %1, %2" : "=v"(r) : "v"(lo), "v"(hi)); return r; }
;     __device__ __forceinline__ void operator()(const f32x4 (&acc)[2][2][4][2], const Unit& u, int wr, int wc, int fr, int fq) const {
;         const int row0 = u.pm * BM + wr * 64 + fr, col0 = u.pn * HALF + wc * 32 + 8 * fq;
; #pragma unroll
;         for (int ai = 0; ai < 2; ++ai)
; #pragma unroll
;             for (int m = 0; m < 4; ++m) { bf16_t* rowp = O + (size_t)(row0 + ai * HALF + m * 16) * ldc + col0;
;                 float h[8]; __builtin_amdgcn_sched_barrier(0);
; #pragma unroll
;                 for (int n = 0; n < 2; ++n)
; #pragma unroll
;                     for (int i = 0; i < 4; ++i) { const float g = acc[ai][0][m][n][i], up = acc[ai][1][m][n][i];
;                         h[4 * n + i] = g * __builtin_amdgcn_rcpf(1.0f + __builtin_amdgcn_exp2f(-1.4426950408889634f * g)) * up; }
;                 u32x4 w; w.x = cvt_pk_bf16(h[0], h[1]); w.y = cvt_pk_bf16(h[2], h[3]); w.z = cvt_pk_bf16(h[4], h[5]); w.w = cvt_pk_bf16(h[6], h[7]);
;                 *(u32x4*)rowp = w; }
.LBB0_1493:
	v_lshl_add_u32 v146, s3, 8, v142
	v_lshl_or_b32 v148, s2, 7, v144
	v_mov_b64_e32 v[140:141], s[74:75]
	v_ashrrev_i32_e32 v149, 31, v148
	v_mad_i64_i32 v[150:151], s[2:3], v146, s39, v[140:141]
	v_lshlrev_b64 v[194:195], 1, v[148:149]
	v_lshl_add_u64 v[200:201], v[150:151], 0, v[194:195]
	s_mov_b32 s23, 0
	v_mul_f32_e32 v152, 0xbfb8aa3b, v126
	v_mul_f32_e32 v153, 0xbfb8aa3b, v127
	v_mul_f32_e32 v154, 0xbfb8aa3b, v128
	v_mul_f32_e32 v155, 0xbfb8aa3b, v129
	v_mul_f32_e32 v156, 0xbfb8aa3b, v118
	v_mul_f32_e32 v157, 0xbfb8aa3b, v119
	v_mul_f32_e32 v158, 0xbfb8aa3b, v120
	v_mul_f32_e32 v159, 0xbfb8aa3b, v121
	v_exp_f32_e32 v152, v152
	v_exp_f32_e32 v153, v153
	v_exp_f32_e32 v154, v154
	v_exp_f32_e32 v155, v155
	v_exp_f32_e32 v156, v156
	v_exp_f32_e32 v157, v157
	v_exp_f32_e32 v158, v158
	v_exp_f32_e32 v159, v159
	v_add_f32_e32 v152, 1.0, v152
	v_add_f32_e32 v153, 1.0, v153
	v_add_f32_e32 v154, 1.0, v154
	v_add_f32_e32 v155, 1.0, v155
	v_add_f32_e32 v156, 1.0, v156
	v_add_f32_e32 v157, 1.0, v157
	v_add_f32_e32 v158, 1.0, v158
	v_add_f32_e32 v159, 1.0, v159
	v_rcp_f32_e32 v152, v152
	v_rcp_f32_e32 v153, v153
	v_rcp_f32_e32 v154, v154
	v_rcp_f32_e32 v155, v155
	v_rcp_f32_e32 v156, v156
	v_rcp_f32_e32 v157, v157
	v_rcp_f32_e32 v158, v158
	v_rcp_f32_e32 v159, v159
	v_mul_f32_e32 v152, v126, v152
	v_mul_f32_e32 v153, v127, v153
	v_mul_f32_e32 v154, v128, v154
	v_mul_f32_e32 v155, v129, v155
	v_mul_f32_e32 v156, v118, v156
	v_mul_f32_e32 v157, v119, v157
	v_mul_f32_e32 v158, v120, v158
	v_mul_f32_e32 v159, v121, v159
	v_mul_f32_e32 v152, v152, v122
	v_mul_f32_e32 v153, v153, v123
	v_mul_f32_e32 v154, v154, v124
	v_mul_f32_e32 v155, v155, v125
	v_mul_f32_e32 v156, v156, v114
	v_mul_f32_e32 v157, v157, v115
	v_mul_f32_e32 v158, v158, v116
	v_mul_f32_e32 v159, v159, v117
	v_cvt_pk_bf16_f32 v168, v152, v153
	v_cvt_pk_bf16_f32 v169, v154, v155
	v_cvt_pk_bf16_f32 v170, v156, v157
	v_cvt_pk_bf16_f32 v171, v158, v159
	global_store_dwordx4 v[200:201], v[168:171], off
	v_mul_f32_e32 v160, 0xbfb8aa3b, v110
	v_mul_f32_e32 v161, 0xbfb8aa3b, v111
	v_mul_f32_e32 v162, 0xbfb8aa3b, v112
	v_mul_f32_e32 v163, 0xbfb8aa3b, v113
	v_mul_f32_e32 v164, 0xbfb8aa3b, v102
	v_mul_f32_e32 v165, 0xbfb8aa3b, v103
	v_mul_f32_e32 v166, 0xbfb8aa3b, v104
	v_mul_f32_e32 v167, 0xbfb8aa3b, v105
	s_mul_i32 s22, s39, 0x10
	v_exp_f32_e32 v160, v160
	v_exp_f32_e32 v161, v161
	v_exp_f32_e32 v162, v162
	v_exp_f32_e32 v163, v163
	v_exp_f32_e32 v164, v164
	v_exp_f32_e32 v165, v165
	v_exp_f32_e32 v166, v166
	v_exp_f32_e32 v167, v167
	v_lshl_add_u64 v[198:199], v[200:201], 0, s[22:23]
	v_add_f32_e32 v160, 1.0, v160
	v_add_f32_e32 v161, 1.0, v161
	v_add_f32_e32 v162, 1.0, v162
	v_add_f32_e32 v163, 1.0, v163
	v_add_f32_e32 v164, 1.0, v164
	v_add_f32_e32 v165, 1.0, v165
	v_add_f32_e32 v166, 1.0, v166
	v_add_f32_e32 v167, 1.0, v167
	v_rcp_f32_e32 v160, v160
	v_rcp_f32_e32 v161, v161
	v_rcp_f32_e32 v162, v162
	v_rcp_f32_e32 v163, v163
	v_rcp_f32_e32 v164, v164
	v_rcp_f32_e32 v165, v165
	v_rcp_f32_e32 v166, v166
	v_rcp_f32_e32 v167, v167
	v_mul_f32_e32 v160, v110, v160
	v_mul_f32_e32 v161, v111, v161
	v_mul_f32_e32 v162, v112, v162
	v_mul_f32_e32 v163, v113, v163
	v_mul_f32_e32 v164, v102, v164
	v_mul_f32_e32 v165, v103, v165
	v_mul_f32_e32 v166, v104, v166
	v_mul_f32_e32 v167, v105, v167
	v_mul_f32_e32 v160, v160, v106
	v_mul_f32_e32 v161, v161, v107
	v_mul_f32_e32 v162, v162, v108
	v_mul_f32_e32 v163, v163, v109
	v_mul_f32_e32 v164, v164, v98
	v_mul_f32_e32 v165, v165, v99
	v_mul_f32_e32 v166, v166, v100
	v_mul_f32_e32 v167, v167, v101
	v_cvt_pk_bf16_f32 v172, v160, v161
	v_cvt_pk_bf16_f32 v173, v162, v163
	v_cvt_pk_bf16_f32 v174, v164, v165
	v_cvt_pk_bf16_f32 v175, v166, v167
	global_store_dwordx4 v[198:199], v[172:175], off
	v_mul_f32_e32 v152, 0xbfb8aa3b, v94
	v_mul_f32_e32 v153, 0xbfb8aa3b, v95
	v_mul_f32_e32 v154, 0xbfb8aa3b, v96
	v_mul_f32_e32 v155, 0xbfb8aa3b, v97
	v_mul_f32_e32 v156, 0xbfb8aa3b, v86
	v_mul_f32_e32 v157, 0xbfb8aa3b, v87
	v_mul_f32_e32 v158, 0xbfb8aa3b, v88
	v_mul_f32_e32 v159, 0xbfb8aa3b, v89
	s_mul_i32 s22, s39, 0x20
	v_exp_f32_e32 v152, v152
	v_exp_f32_e32 v153, v153
	v_exp_f32_e32 v154, v154
	v_exp_f32_e32 v155, v155
	v_exp_f32_e32 v156, v156
	v_exp_f32_e32 v157, v157
	v_exp_f32_e32 v158, v158
	v_exp_f32_e32 v159, v159
	v_lshl_add_u64 v[196:197], v[200:201], 0, s[22:23]
	v_add_f32_e32 v152, 1.0, v152
	v_add_f32_e32 v153, 1.0, v153
	v_add_f32_e32 v154, 1.0, v154
	v_add_f32_e32 v155, 1.0, v155
	v_add_f32_e32 v156, 1.0, v156
	v_add_f32_e32 v157, 1.0, v157
	v_add_f32_e32 v158, 1.0, v158
	v_add_f32_e32 v159, 1.0, v159
	v_rcp_f32_e32 v152, v152
	v_rcp_f32_e32 v153, v153
	v_rcp_f32_e32 v154, v154
	v_rcp_f32_e32 v155, v155
	v_rcp_f32_e32 v156, v156
	v_rcp_f32_e32 v157, v157
	v_rcp_f32_e32 v158, v158
	v_rcp_f32_e32 v159, v159
	v_mul_f32_e32 v152, v94, v152
	v_mul_f32_e32 v153, v95, v153
	v_mul_f32_e32 v154, v96, v154
	v_mul_f32_e32 v155, v97, v155
	v_mul_f32_e32 v156, v86, v156
	v_mul_f32_e32 v157, v87, v157
	v_mul_f32_e32 v158, v88, v158
	v_mul_f32_e32 v159, v89, v159
	v_mul_f32_e32 v152, v152, v90
	v_mul_f32_e32 v153, v153, v91
	v_mul_f32_e32 v154, v154, v92
	v_mul_f32_e32 v155, v155, v93
	v_mul_f32_e32 v156, v156, v82
	v_mul_f32_e32 v157, v157, v83
	v_mul_f32_e32 v158, v158, v84
	v_mul_f32_e32 v159, v159, v85
	v_cvt_pk_bf16_f32 v168, v152, v153
	v_cvt_pk_bf16_f32 v169, v154, v155
	v_cvt_pk_bf16_f32 v170, v156, v157
	v_cvt_pk_bf16_f32 v171, v158, v159
	global_store_dwordx4 v[196:197], v[168:171], off
	v_mul_f32_e32 v160, 0xbfb8aa3b, v78
	v_mul_f32_e32 v161, 0xbfb8aa3b, v79
	v_mul_f32_e32 v162, 0xbfb8aa3b, v80
	v_mul_f32_e32 v163, 0xbfb8aa3b, v81
	v_mul_f32_e32 v164, 0xbfb8aa3b, v70
; __device__ __forceinline__ unsigned cvt_pk_bf16(float lo, float hi) { unsigned r; asm volatile("v_cvt_pk_bf16_f32 %0, %1, %2" : "=v"(r) : "v"(lo), "v"(hi)); return r; }
;     __device__ __forceinline__ void operator()(const f32x4 (&acc)[2][2][4][2], const Unit& u, int wr, int wc, int fr, int fq) const {
;         const int row0 = u.pm * BM + wr * 64 + fr, col0 = u.pn * HALF + wc * 32 + 8 * fq;
; #pragma unroll
;         for (int ai = 0; ai < 2; ++ai)
; #pragma unroll
;             for (int m = 0; m < 4; ++m) { bf16_t* rowp = O + (size_t)(row0 + ai * HALF + m * 16) * ldc + col0;
;                 float h[8]; __builtin_amdgcn_sched_barrier(0);
; #pragma unroll
;                 for (int n = 0; n < 2; ++n)
; #pragma unroll
;                     for (int i = 0; i < 4; ++i) { const float g = acc[ai][0][m][n][i], up = acc[ai][1][m][n][i];
;                         h[4 * n + i] = g * __builtin_amdgcn_rcpf(1.0f + __builtin_amdgcn_exp2f(-1.4426950408889634f * g)) * up; }
;                 u32x4 w; w.x = cvt_pk_bf16(h[0], h[1]); w.y = cvt_pk_bf16(h[2], h[3]); w.z = cvt_pk_bf16(h[4], h[5]); w.w = cvt_pk_bf16(h[6], h[7]);
;                 *(u32x4*)rowp = w; }
	v_mul_f32_e32 v165, 0xbfb8aa3b, v71
	v_mul_f32_e32 v166, 0xbfb8aa3b, v72
	v_mul_f32_e32 v167, 0xbfb8aa3b, v73
	s_mul_i32 s22, s39, 0x30
	v_exp_f32_e32 v160, v160
	v_exp_f32_e32 v161, v161
	v_exp_f32_e32 v162, v162
	v_exp_f32_e32 v163, v163
	v_exp_f32_e32 v164, v164
	v_exp_f32_e32 v165, v165
	v_exp_f32_e32 v166, v166
	v_exp_f32_e32 v167, v167
	v_lshl_add_u64 v[198:199], v[200:201], 0, s[22:23]
	v_add_f32_e32 v160, 1.0, v160
	v_add_f32_e32 v161, 1.0, v161
	v_add_f32_e32 v162, 1.0, v162
	v_add_f32_e32 v163, 1.0, v163
	v_add_f32_e32 v164, 1.0, v164
	v_add_f32_e32 v165, 1.0, v165
	v_add_f32_e32 v166, 1.0, v166
	v_add_f32_e32 v167, 1.0, v167
	v_rcp_f32_e32 v160, v160
	v_rcp_f32_e32 v161, v161
	v_rcp_f32_e32 v162, v162
	v_rcp_f32_e32 v163, v163
	v_rcp_f32_e32 v164, v164
	v_rcp_f32_e32 v165, v165
	v_rcp_f32_e32 v166, v166
	v_rcp_f32_e32 v167, v167
	v_mul_f32_e32 v160, v78, v160
	v_mul_f32_e32 v161, v79, v161
	v_mul_f32_e32 v162, v80, v162
	v_mul_f32_e32 v163, v81, v163
	v_mul_f32_e32 v164, v70, v164
	v_mul_f32_e32 v165, v71, v165
	v_mul_f32_e32 v166, v72, v166
	v_mul_f32_e32 v167, v73, v167
	v_mul_f32_e32 v160, v160, v74
	v_mul_f32_e32 v161, v161, v75
	v_mul_f32_e32 v162, v162, v76
	v_mul_f32_e32 v163, v163, v77
	v_mul_f32_e32 v164, v164, v66
	v_mul_f32_e32 v165, v165, v67
	v_mul_f32_e32 v166, v166, v68
	v_mul_f32_e32 v167, v167, v69
	v_cvt_pk_bf16_f32 v172, v160, v161
	v_cvt_pk_bf16_f32 v173, v162, v163
	v_cvt_pk_bf16_f32 v174, v164, v165
	v_cvt_pk_bf16_f32 v175, v166, v167
	global_store_dwordx4 v[198:199], v[172:175], off
	v_mul_f32_e32 v152, 0xbfb8aa3b, v62
	v_mul_f32_e32 v153, 0xbfb8aa3b, v63
	v_mul_f32_e32 v154, 0xbfb8aa3b, v64
	v_mul_f32_e32 v155, 0xbfb8aa3b, v65
	v_mul_f32_e32 v156, 0xbfb8aa3b, v54
	v_mul_f32_e32 v157, 0xbfb8aa3b, v55
	v_mul_f32_e32 v158, 0xbfb8aa3b, v56
	v_mul_f32_e32 v159, 0xbfb8aa3b, v57
	s_mul_i32 s22, s39, 0x80
	v_exp_f32_e32 v152, v152
	v_exp_f32_e32 v153, v153
	v_exp_f32_e32 v154, v154
	v_exp_f32_e32 v155, v155
	v_exp_f32_e32 v156, v156
	v_exp_f32_e32 v157, v157
	v_exp_f32_e32 v158, v158
	v_exp_f32_e32 v159, v159
	v_lshl_add_u64 v[196:197], v[200:201], 0, s[22:23]
	v_add_f32_e32 v152, 1.0, v152
	v_add_f32_e32 v153, 1.0, v153
	v_add_f32_e32 v154, 1.0, v154
	v_add_f32_e32 v155, 1.0, v155
	v_add_f32_e32 v156, 1.0, v156
	v_add_f32_e32 v157, 1.0, v157
	v_add_f32_e32 v158, 1.0, v158
	v_add_f32_e32 v159, 1.0, v159
	v_rcp_f32_e32 v152, v152
	v_rcp_f32_e32 v153, v153
	v_rcp_f32_e32 v154, v154
	v_rcp_f32_e32 v155, v155
	v_rcp_f32_e32 v156, v156
	v_rcp_f32_e32 v157, v157
	v_rcp_f32_e32 v158, v158
	v_rcp_f32_e32 v159, v159
	v_mul_f32_e32 v152, v62, v152
	v_mul_f32_e32 v153, v63, v153
	v_mul_f32_e32 v154, v64, v154
	v_mul_f32_e32 v155, v65, v155
	v_mul_f32_e32 v156, v54, v156
	v_mul_f32_e32 v157, v55, v157
	v_mul_f32_e32 v158, v56, v158
	v_mul_f32_e32 v159, v57, v159
	v_mul_f32_e32 v152, v152, v58
	v_mul_f32_e32 v153, v153, v59
	v_mul_f32_e32 v154, v154, v60
	v_mul_f32_e32 v155, v155, v61
	v_mul_f32_e32 v156, v156, v50
	v_mul_f32_e32 v157, v157, v51
	v_mul_f32_e32 v158, v158, v52
	v_mul_f32_e32 v159, v159, v53
	v_cvt_pk_bf16_f32 v168, v152, v153
	v_cvt_pk_bf16_f32 v169, v154, v155
	v_cvt_pk_bf16_f32 v170, v156, v157
	v_cvt_pk_bf16_f32 v171, v158, v159
	global_store_dwordx4 v[196:197], v[168:171], off
	v_mul_f32_e32 v160, 0xbfb8aa3b, v46
	v_mul_f32_e32 v161, 0xbfb8aa3b, v47
	v_mul_f32_e32 v162, 0xbfb8aa3b, v48
	v_mul_f32_e32 v163, 0xbfb8aa3b, v49
	v_mul_f32_e32 v164, 0xbfb8aa3b, v38
	v_mul_f32_e32 v165, 0xbfb8aa3b, v39
	v_mul_f32_e32 v166, 0xbfb8aa3b, v40
	v_mul_f32_e32 v167, 0xbfb8aa3b, v41
	s_mul_i32 s22, s39, 0x90
	v_exp_f32_e32 v160, v160
	v_exp_f32_e32 v161, v161
	v_exp_f32_e32 v162, v162
	v_exp_f32_e32 v163, v163
	v_exp_f32_e32 v164, v164
	v_exp_f32_e32 v165, v165
	v_exp_f32_e32 v166, v166
	v_exp_f32_e32 v167, v167
	v_lshl_add_u64 v[198:199], v[200:201], 0, s[22:23]
	v_add_f32_e32 v160, 1.0, v160
	v_add_f32_e32 v161, 1.0, v161
	v_add_f32_e32 v162, 1.0, v162
	v_add_f32_e32 v163, 1.0, v163
	v_add_f32_e32 v164, 1.0, v164
	v_add_f32_e32 v165, 1.0, v165
	v_add_f32_e32 v166, 1.0, v166
	v_add_f32_e32 v167, 1.0, v167
	v_rcp_f32_e32 v160, v160
	v_rcp_f32_e32 v161, v161
	v_rcp_f32_e32 v162, v162
	v_rcp_f32_e32 v163, v163
	v_rcp_f32_e32 v164, v164
	v_rcp_f32_e32 v165, v165
	v_rcp_f32_e32 v166, v166
	v_rcp_f32_e32 v167, v167
; __device__ __forceinline__ unsigned cvt_pk_bf16(float lo, float hi) { unsigned r; asm volatile("v_cvt_pk_bf16_f32 %0, %1, %2" : "=v"(r) : "v"(lo), "v"(hi)); return r; }
; #define PG8_BAR __builtin_amdgcn_s_barrier()
;     __device__ __forceinline__ void operator()(const f32x4 (&acc)[2][2][4][2], const Unit& u, int wr, int wc, int fr, int fq) const {
;         const int row0 = u.pm * BM + wr * 64 + fr, col0 = u.pn * HALF + wc * 32 + 8 * fq;
; #pragma unroll
;         for (int ai = 0; ai < 2; ++ai)
; #pragma unroll
;             for (int m = 0; m < 4; ++m) { bf16_t* rowp = O + (size_t)(row0 + ai * HALF + m * 16) * ldc + col0;
;                 float h[8]; __builtin_amdgcn_sched_barrier(0);
; #pragma unroll
;                 for (int n = 0; n < 2; ++n)
; #pragma unroll
;                     for (int i = 0; i < 4; ++i) { const float g = acc[ai][0][m][n][i], up = acc[ai][1][m][n][i];
;                         h[4 * n + i] = g * __builtin_amdgcn_rcpf(1.0f + __builtin_amdgcn_exp2f(-1.4426950408889634f * g)) * up; }
;                 u32x4 w; w.x = cvt_pk_bf16(h[0], h[1]); w.y = cvt_pk_bf16(h[2], h[3]); w.z = cvt_pk_bf16(h[4], h[5]); w.w = cvt_pk_bf16(h[6], h[7]);
;                 *(u32x4*)rowp = w; }
; template <class Epi, class Sched, bool ALIGN_EPI = false, bool SP2 = false>
; __device__ __forceinline__ void gemm_phase(PG8_LAS unsigned char* lds, const Gemm g, const Sched& S, const Epi& E) {
;     ...
;         if constexpr (!Epi::AFTER_DRAIN) { E(acc, cur, wr, wc, fr, fq); S.done(cur); }
;         if (!has_next) break;
; #pragma unroll
;         for (int a = 0; a < 2; ++a)
; #pragma unroll
;             for (int b = 0; b < 2; ++b)
; #pragma unroll
;                 for (int m = 0; m < 4; ++m)
; #pragma unroll
;                     for (int n = 0; n < 2; ++n) acc[a][b][m][n] = (f32x4){0.f, 0.f, 0.f, 0.f};
;         cur = nxt; cA = nA; cB = nB; ++ui;
;         if constexpr (ALIGN_EPI) { if (wr == 1) PG8_BAR; }
	v_mul_f32_e32 v160, v46, v160
	v_mul_f32_e32 v161, v47, v161
	v_mul_f32_e32 v162, v48, v162
	v_mul_f32_e32 v163, v49, v163
	v_mul_f32_e32 v164, v38, v164
	v_mul_f32_e32 v165, v39, v165
	v_mul_f32_e32 v166, v40, v166
	v_mul_f32_e32 v167, v41, v167
	v_mul_f32_e32 v160, v160, v42
	v_mul_f32_e32 v161, v161, v43
	v_mul_f32_e32 v162, v162, v44
	v_mul_f32_e32 v163, v163, v45
	v_mul_f32_e32 v164, v164, v34
	v_mul_f32_e32 v165, v165, v35
	v_mul_f32_e32 v166, v166, v36
	v_mul_f32_e32 v167, v167, v37
	v_cvt_pk_bf16_f32 v172, v160, v161
	v_cvt_pk_bf16_f32 v173, v162, v163
	v_cvt_pk_bf16_f32 v174, v164, v165
	v_cvt_pk_bf16_f32 v175, v166, v167
	global_store_dwordx4 v[198:199], v[172:175], off
	v_mul_f32_e32 v152, 0xbfb8aa3b, v30
	v_mul_f32_e32 v153, 0xbfb8aa3b, v31
	v_mul_f32_e32 v154, 0xbfb8aa3b, v32
	v_mul_f32_e32 v155, 0xbfb8aa3b, v33
	v_mul_f32_e32 v156, 0xbfb8aa3b, v22
	v_mul_f32_e32 v157, 0xbfb8aa3b, v23
	v_mul_f32_e32 v158, 0xbfb8aa3b, v24
	v_mul_f32_e32 v159, 0xbfb8aa3b, v25
	s_mul_i32 s22, s39, 0xa0
	v_exp_f32_e32 v152, v152
	v_exp_f32_e32 v153, v153
	v_exp_f32_e32 v154, v154
	v_exp_f32_e32 v155, v155
	v_exp_f32_e32 v156, v156
	v_exp_f32_e32 v157, v157
	v_exp_f32_e32 v158, v158
	v_exp_f32_e32 v159, v159
	v_lshl_add_u64 v[196:197], v[200:201], 0, s[22:23]
	v_add_f32_e32 v152, 1.0, v152
	v_add_f32_e32 v153, 1.0, v153
	v_add_f32_e32 v154, 1.0, v154
	v_add_f32_e32 v155, 1.0, v155
	v_add_f32_e32 v156, 1.0, v156
	v_add_f32_e32 v157, 1.0, v157
	v_add_f32_e32 v158, 1.0, v158
	v_add_f32_e32 v159, 1.0, v159
	v_rcp_f32_e32 v152, v152
	v_rcp_f32_e32 v153, v153
	v_rcp_f32_e32 v154, v154
	v_rcp_f32_e32 v155, v155
	v_rcp_f32_e32 v156, v156
	v_rcp_f32_e32 v157, v157
	v_rcp_f32_e32 v158, v158
	v_rcp_f32_e32 v159, v159
	v_mul_f32_e32 v152, v30, v152
	v_mul_f32_e32 v153, v31, v153
	v_mul_f32_e32 v154, v32, v154
	v_mul_f32_e32 v155, v33, v155
	v_mul_f32_e32 v156, v22, v156
	v_mul_f32_e32 v157, v23, v157
	v_mul_f32_e32 v158, v24, v158
	v_mul_f32_e32 v159, v25, v159
	v_mul_f32_e32 v152, v152, v26
	v_mul_f32_e32 v153, v153, v27
	v_mul_f32_e32 v154, v154, v28
	v_mul_f32_e32 v155, v155, v29
	v_mul_f32_e32 v156, v156, v18
	v_mul_f32_e32 v157, v157, v19
	v_mul_f32_e32 v158, v158, v20
	v_mul_f32_e32 v159, v159, v21
	v_cvt_pk_bf16_f32 v168, v152, v153
	v_cvt_pk_bf16_f32 v169, v154, v155
	v_cvt_pk_bf16_f32 v170, v156, v157
	v_cvt_pk_bf16_f32 v171, v158, v159
	global_store_dwordx4 v[196:197], v[168:171], off
	v_mul_f32_e32 v160, 0xbfb8aa3b, v14
	v_mul_f32_e32 v161, 0xbfb8aa3b, v15
	v_mul_f32_e32 v162, 0xbfb8aa3b, v16
	v_mul_f32_e32 v163, 0xbfb8aa3b, v17
	v_mul_f32_e32 v164, 0xbfb8aa3b, v10
	v_mul_f32_e32 v165, 0xbfb8aa3b, v11
	v_mul_f32_e32 v166, 0xbfb8aa3b, v12
	v_mul_f32_e32 v167, 0xbfb8aa3b, v13
	s_mul_i32 s22, s39, 0xb0
	v_exp_f32_e32 v160, v160
	v_exp_f32_e32 v161, v161
	v_exp_f32_e32 v162, v162
	v_exp_f32_e32 v163, v163
	v_exp_f32_e32 v164, v164
	v_exp_f32_e32 v165, v165
	v_exp_f32_e32 v166, v166
	v_exp_f32_e32 v167, v167
	v_lshl_add_u64 v[198:199], v[200:201], 0, s[22:23]
	v_add_f32_e32 v160, 1.0, v160
	v_add_f32_e32 v161, 1.0, v161
	v_add_f32_e32 v162, 1.0, v162
	v_add_f32_e32 v163, 1.0, v163
	v_add_f32_e32 v164, 1.0, v164
	v_add_f32_e32 v165, 1.0, v165
	v_add_f32_e32 v166, 1.0, v166
	v_add_f32_e32 v167, 1.0, v167
	v_rcp_f32_e32 v160, v160
	v_rcp_f32_e32 v161, v161
	v_rcp_f32_e32 v162, v162
	v_rcp_f32_e32 v163, v163
	v_rcp_f32_e32 v164, v164
	v_rcp_f32_e32 v165, v165
	v_rcp_f32_e32 v166, v166
	v_rcp_f32_e32 v167, v167
	v_mul_f32_e32 v160, v14, v160
	v_mul_f32_e32 v161, v15, v161
	v_mul_f32_e32 v162, v16, v162
	v_mul_f32_e32 v163, v17, v163
	v_mul_f32_e32 v164, v10, v164
	v_mul_f32_e32 v165, v11, v165
	v_mul_f32_e32 v166, v12, v166
	v_mul_f32_e32 v167, v13, v167
	v_mul_f32_e32 v160, v160, v6
	v_mul_f32_e32 v161, v161, v7
	v_mul_f32_e32 v162, v162, v8
	v_mul_f32_e32 v163, v163, v9
	v_mul_f32_e32 v164, v164, v2
	v_mul_f32_e32 v165, v165, v3
	v_mul_f32_e32 v166, v166, v4
	v_mul_f32_e32 v167, v167, v5
	v_cvt_pk_bf16_f32 v172, v160, v161
	v_cvt_pk_bf16_f32 v173, v162, v163
	v_cvt_pk_bf16_f32 v174, v164, v165
	v_cvt_pk_bf16_f32 v175, v166, v167
	s_andn2_b64 vcc, exec, s[40:41]
	s_mov_b64 s[30:31], -1
	s_mov_b32 s25, s61
	global_store_dwordx4 v[198:199], v[172:175], off
	s_cbranch_vccnz .LBB0_1486
	s_andn2_b64 vcc, exec, s[10:11]
	s_cbranch_vccnz .LBB0_1485
	s_barrier
	s_branch .LBB0_1485
